# norm tail chunk queues split into 4 shards (one counter word per quarter of the workgroups) to cut same-address atomic serialization
# baseline (speedup 1.0000x reference)
.LBB0_730:
	v_readlane_b32 s98, v254, 39
	v_readlane_b32 s99, v254, 40
	s_mov_b64 vcc, exec
	s_and_b64 exec, exec, s[98:99]
	s_and_b32 s100, s101, 3
	s_lshl_b32 s100, s100, 6
	v_mov_b32_e32 v251, s100
	v_mov_b32_e32 v252, 1
	global_atomic_add v253, v251, v252, s[58:59] sc0
	s_mov_b64 exec, vcc
	s_mov_b32 s99, 0
	s_waitcnt vmcnt(0)
	s_barrier
	s_mov_b64 s[0:1], exec
	v_readlane_b32 s6, v254, 39
	v_readlane_b32 s7, v254, 40
	s_and_b64 s[6:7], s[0:1], s[6:7]
	s_mov_b64 exec, s[6:7]
	s_cbranch_execz .LBB0_768
	s_cmp_lt_i32 s3, 0
	s_cbranch_scc1 .LBB0_735
	s_mov_b64 s[8:9], exec
	v_mbcnt_lo_u32_b32 v32, s8, 0
	v_mbcnt_hi_u32_b32 v32, s9, v32
	v_cmp_eq_u32_e32 vcc, 0, v32
	s_and_saveexec_b64 s[6:7], vcc
	s_cbranch_execz .LBB0_734
	s_lshl_b32 s68, s3, 6
	s_lshl_b64 s[14:15], s[68:69], 2
	v_readlane_b32 s3, v255, 2
	s_add_u32 s14, s3, s14
	v_readlane_b32 s3, v255, 3
	s_addc_u32 s15, s3, s15
	s_bcnt1_i32_b64 s3, s[8:9]
	v_mov_b32_e32 v32, s3
	global_atomic_add v61, v32, s[14:15]

.LBB0_735:
	s_mov_b64 s[8:9], exec
	v_mbcnt_lo_u32_b32 v32, s8, 0
	v_mbcnt_hi_u32_b32 v32, s9, v32
	v_cmp_eq_u32_e32 vcc, 0, v32
	s_and_saveexec_b64 s[6:7], vcc
	s_cbranch_execz .LBB0_737
	s_bcnt1_i32_b64 s3, s[8:9]
	s_and_b32 s100, s101, 3
	v_lshl_or_b32 v33, v253, 2, s100

.LBB0_1354:
	v_readlane_b32 s98, v254, 39
	v_readlane_b32 s99, v254, 40
	s_mov_b64 vcc, exec
	s_and_b64 exec, exec, s[98:99]
	s_and_b32 s100, s101, 3
	s_lshl_b32 s100, s100, 6
	v_mov_b32_e32 v251, s100
	v_mov_b32_e32 v252, 1
	global_atomic_add v253, v251, v252, s[58:59] sc0
	s_mov_b64 exec, vcc
	s_mov_b32 s99, 0
	s_waitcnt vmcnt(0)
	s_barrier
	s_mov_b64 s[0:1], exec
	v_readlane_b32 s6, v254, 39
	v_readlane_b32 s7, v254, 40
	s_and_b64 s[6:7], s[0:1], s[6:7]
	s_mov_b64 exec, s[6:7]
	s_cbranch_execz .LBB0_1392
	s_cmp_lt_i32 s3, 0
	s_cbranch_scc1 .LBB0_1359
	s_mov_b64 s[8:9], exec
	v_mbcnt_lo_u32_b32 v42, s8, 0
	v_mbcnt_hi_u32_b32 v42, s9, v42
	v_cmp_eq_u32_e32 vcc, 0, v42
	s_and_saveexec_b64 s[6:7], vcc
	s_cbranch_execz .LBB0_1358
	s_lshl_b32 s56, s3, 6
	s_lshl_b64 s[10:11], s[56:57], 2
	v_readlane_b32 s3, v255, 2
	s_add_u32 s10, s3, s10
	v_readlane_b32 s3, v255, 3
	s_addc_u32 s11, s3, s11
	s_bcnt1_i32_b64 s3, s[8:9]
	v_mov_b32_e32 v42, s3
	global_atomic_add v43, v42, s[10:11]

.LBB0_1359:
	s_mov_b64 s[8:9], exec
	v_mbcnt_lo_u32_b32 v42, s8, 0
	v_mbcnt_hi_u32_b32 v42, s9, v42
	v_cmp_eq_u32_e32 vcc, 0, v42
	s_and_saveexec_b64 s[6:7], vcc
	s_cbranch_execz .LBB0_1361
	s_bcnt1_i32_b64 s3, s[8:9]
	s_and_b32 s100, s101, 3
	v_lshl_or_b32 v44, v253, 2, s100

.LBB0_1967:
	v_readlane_b32 s98, v254, 39
	v_readlane_b32 s99, v254, 40
	s_mov_b64 vcc, exec
	s_and_b64 exec, exec, s[98:99]
	s_and_b32 s100, s101, 3
	s_lshl_b32 s100, s100, 6
	v_mov_b32_e32 v251, s100
	v_mov_b32_e32 v252, 1
	global_atomic_add v253, v251, v252, s[36:37] sc0
	s_mov_b64 exec, vcc
	s_mov_b32 s99, 0
	s_waitcnt vmcnt(0)
	s_barrier
	s_mov_b64 s[0:1], exec
	v_readlane_b32 s6, v254, 39
	v_readlane_b32 s7, v254, 40
	s_and_b64 s[6:7], s[0:1], s[6:7]
	s_mov_b64 exec, s[6:7]
	s_cbranch_execz .LBB0_2005
	s_cmp_lt_i32 s3, 0
	s_cbranch_scc1 .LBB0_1972
	s_mov_b64 s[10:11], exec
	v_mbcnt_lo_u32_b32 v42, s10, 0
	v_mbcnt_hi_u32_b32 v42, s11, v42
	v_cmp_eq_u32_e32 vcc, 0, v42
	s_and_saveexec_b64 s[6:7], vcc
	s_cbranch_execz .LBB0_1971
	s_lshl_b32 s14, s3, 6
	s_lshl_b64 s[12:13], s[14:15], 2
	v_readlane_b32 s3, v254, 47
	s_add_u32 s12, s3, s12
	v_readlane_b32 s3, v255, 2
	s_addc_u32 s13, s3, s13
	s_bcnt1_i32_b64 s3, s[10:11]
	v_mov_b32_e32 v42, s3
	global_atomic_add v43, v42, s[12:13]

.LBB0_1972:
	s_mov_b64 s[10:11], exec
	v_mbcnt_lo_u32_b32 v42, s10, 0
	v_mbcnt_hi_u32_b32 v42, s11, v42
	v_cmp_eq_u32_e32 vcc, 0, v42
	s_and_saveexec_b64 s[6:7], vcc
	s_cbranch_execz .LBB0_1974
	s_bcnt1_i32_b64 s3, s[10:11]
	s_and_b32 s100, s101, 3
	v_lshl_or_b32 v44, v253, 2, s100

.LBB0_2395:
	v_readlane_b32 s98, v254, 39
	v_readlane_b32 s99, v254, 40
	s_mov_b64 vcc, exec
	s_and_b64 exec, exec, s[98:99]
	s_and_b32 s100, s101, 3
	s_lshl_b32 s100, s100, 6
	v_mov_b32_e32 v251, s100
	v_mov_b32_e32 v252, 1
	global_atomic_add v253, v251, v252, s[6:7] sc0
	s_mov_b64 exec, vcc
	s_mov_b32 s99, 0
	s_waitcnt vmcnt(0)
	s_barrier
	s_mov_b64 s[4:5], exec
	v_readlane_b32 s8, v254, 39
	v_readlane_b32 s9, v254, 40
	s_and_b64 s[8:9], s[4:5], s[8:9]
	s_mov_b64 exec, s[8:9]
	s_cbranch_execz .LBB0_2429
	s_mov_b64 s[12:13], exec
	v_mbcnt_lo_u32_b32 v22, s12, 0
	v_mbcnt_hi_u32_b32 v22, s13, v22
	v_cmp_eq_u32_e32 vcc, 0, v22
	s_and_saveexec_b64 s[8:9], vcc
	s_cbranch_execz .LBB0_2398
	s_bcnt1_i32_b64 s2, s[12:13]
	s_and_b32 s100, s101, 3
	v_lshl_or_b32 v24, v253, 2, s100
